# DMA macro m0 save/restore removed; grid-barrier L1 invalidate issued at arrival instead of after release
# speedup vs baseline: 1.0149x; 1.0149x over previous
.LBB0_123:
	s_lshl_b32 s2, s41, 6
	s_lshl_b32 s3, s41, 8
	s_add_u32 s27, s34, s3
	s_addc_u32 s26, s35, 0
	v_mov_b32_e32 v1, s27
	v_add_co_u32_e32 v4, vcc, 0x1000, v1
	v_mov_b32_e32 v1, s26
	s_nop 0
	v_addc_co_u32_e32 v5, vcc, 0, v1, vcc
	v_mov_b32_e32 v1, 1
	flat_atomic_add v1, v[4:5], v1 offset:1024 sc0
	buffer_inv sc1
	v_cvt_f32_u32_e32 v3, v2
	v_sub_u32_e32 v4, 0, v2
	s_mov_b32 s3, 0
	v_rcp_iflag_f32_e32 v3, v3
	s_nop 0
	v_mul_f32_e32 v3, 0x4f7ffffe, v3
	v_cvt_u32_f32_e32 v3, v3
	v_mul_lo_u32 v4, v4, v3
	v_mul_hi_u32 v4, v3, v4
	v_add_u32_e32 v3, v3, v4
	s_waitcnt vmcnt(0) lgkmcnt(0)
	v_mul_hi_u32 v3, v1, v3
	v_mul_lo_u32 v5, v3, v2
	v_add_u32_e32 v4, 1, v1
	v_sub_u32_e32 v1, v1, v5
	v_add_u32_e32 v6, 1, v3
	v_cmp_ge_u32_e32 vcc, v1, v2
	v_sub_u32_e32 v5, v1, v2
	s_nop 0
	v_cndmask_b32_e32 v3, v3, v6, vcc
	v_cndmask_b32_e32 v1, v1, v5, vcc
	v_add_u32_e32 v5, 1, v3
	v_cmp_ge_u32_e32 vcc, v1, v2
	s_nop 1
	v_cndmask_b32_e32 v1, v3, v5, vcc
	v_mad_u64_u32 v[2:3], s[4:5], v2, v1, v[2:3]
	v_cmp_ne_u32_e32 vcc, v4, v2
	s_and_saveexec_b64 s[4:5], vcc
	s_xor_b64 s[4:5], exec, s[4:5]
	s_cbranch_execz .LBB0_136
	v_mov_b32_e32 v0, s27
	v_add_co_u32_e32 v2, vcc, 0x2000, v0
	v_mov_b32_e32 v0, s26
	s_nop 0
	v_addc_co_u32_e32 v3, vcc, 0, v0, vcc
	flat_load_dword v0, v[2:3] offset:1024 sc1
	s_add_u32 s8, s27, 0x2400
	s_addc_u32 s9, s26, 0
	s_waitcnt vmcnt(0) lgkmcnt(0)
	v_cmp_eq_u32_e32 vcc, v0, v1
	s_and_saveexec_b64 s[6:7], vcc
	s_cbranch_execz .LBB0_135
	s_mov_b32 s24, 1
	s_mov_b64 s[10:11], 0
	s_branch .LBB0_127

.LBB0_135:
	s_or_b64 exec, exec, s[6:7]
	s_waitcnt vmcnt(0) lgkmcnt(0)
	s_nop 0
	s_waitcnt vmcnt(0)

.LBB0_151:
	s_or_b64 exec, exec, s[6:7]
	v_mov_b32_e32 v0, s27
	v_add_co_u32_e32 v0, vcc, 0x2000, v0
	v_mov_b32_e32 v1, s26
	s_nop 0
	v_addc_co_u32_e32 v1, vcc, 0, v1, vcc
	v_mov_b32_e32 v2, 1
	s_waitcnt vmcnt(0) lgkmcnt(0)
	s_nop 0
	flat_atomic_add v[0:1], v2 offset:1024
	s_waitcnt vmcnt(0)

.LBB0_154:
	s_or_b64 exec, exec, s[2:3]
	v_add_co_u32_e32 v0, vcc, 0x2000, v0
	s_waitcnt vmcnt(0) lgkmcnt(0)
	s_nop 0
	v_addc_co_u32_e32 v1, vcc, 0, v1, vcc
	flat_atomic_add v[0:1], v205 offset:1024
	s_waitcnt vmcnt(0)

.LBB0_239:
	v_lshl_add_u64 v[0:1], v[194:195], 2, s[2:3]
	v_add_co_u32_e32 v6, vcc, 0x1000, v0
	v_cvt_f32_u32_e32 v3, v4
	s_nop 0
	v_addc_co_u32_e32 v7, vcc, 0, v1, vcc
	flat_atomic_add v5, v[6:7], v205 offset:1024 sc0
	buffer_inv sc1
	v_rcp_iflag_f32_e32 v3, v3
	v_sub_u32_e32 v6, 0, v4
	v_mul_f32_e32 v3, 0x4f7ffffe, v3
	v_cvt_u32_f32_e32 v3, v3
	v_mul_lo_u32 v6, v6, v3
	v_mul_hi_u32 v6, v3, v6
	v_add_u32_e32 v3, v3, v6
	s_waitcnt vmcnt(0) lgkmcnt(0)
	v_mul_hi_u32 v3, v5, v3
	v_mul_lo_u32 v6, v3, v4
	v_sub_u32_e32 v6, v5, v6
	v_cmp_ge_u32_e32 vcc, v6, v4
	v_add_u32_e32 v7, 1, v3
	s_nop 0
	v_cndmask_b32_e32 v3, v3, v7, vcc
	v_sub_u32_e32 v7, v6, v4
	v_cndmask_b32_e32 v6, v6, v7, vcc
	v_cmp_ge_u32_e32 vcc, v6, v4
	v_add_u32_e32 v6, 1, v3
	s_nop 0
	v_cndmask_b32_e32 v3, v3, v6, vcc
	v_add_u32_e32 v6, 1, v5
	v_mad_u64_u32 v[4:5], s[4:5], v4, v3, v[4:5]
	v_cmp_ne_u32_e32 vcc, v6, v4
	s_and_saveexec_b64 s[4:5], vcc
	s_xor_b64 s[4:5], exec, s[4:5]
	s_cbranch_execz .LBB0_253
	v_add_co_u32_e32 v4, vcc, 0x2000, v0
	s_nop 1
	v_addc_co_u32_e32 v5, vcc, 0, v1, vcc
	flat_load_dword v2, v[4:5] offset:1024 sc1
	s_waitcnt vmcnt(0) lgkmcnt(0)
	v_cmp_eq_u32_e32 vcc, v2, v3
	s_and_saveexec_b64 s[6:7], vcc
	s_cbranch_execz .LBB0_252
	s_mov_b64 s[10:11], 0x2400
	v_lshl_add_u64 v[0:1], v[0:1], 0, s[10:11]
	s_mov_b32 s30, 1
	s_mov_b64 s[10:11], 0
	s_branch .LBB0_243

.LBB0_348:
	s_ashr_i32 s40, s34, 31
	s_add_u32 s42, s10, s34
	s_addc_u32 s40, s11, s40
	s_add_u32 s41, s31, s34
	s_addc_u32 s43, s33, 0
	s_add_u32 s44, s41, 0xdf4000
	s_addc_u32 s41, s43, 0
	s_cmp_lt_i32 s35, 48
	s_cselect_b32 s41, s40, s41
	s_cselect_b32 s40, s42, s44
	s_lshl_b32 s42, s35, 10
	v_lshl_add_u64 v[0:1], s[40:41], 0, v[156:157]
	s_mov_b32 m0, s42
	s_nop 0
	global_load_lds_dwordx4 v[0:1], off
	s_add_i32 s43, s35, 8
	s_addk_i32 s34, 0x2000
	s_cmpk_gt_i32 s35, 0x47
	s_mov_b32 s35, s43
	s_cbranch_scc0 .LBB0_348

.LBB0_443:
	v_lshl_add_u64 v[0:1], v[194:195], 2, s[2:3]
	v_add_co_u32_e32 v6, vcc, 0x1000, v0
	v_cvt_f32_u32_e32 v3, v4
	s_nop 0
	v_addc_co_u32_e32 v7, vcc, 0, v1, vcc
	flat_atomic_add v5, v[6:7], v205 offset:1024 sc0
	buffer_inv sc1
	v_rcp_iflag_f32_e32 v3, v3
	v_sub_u32_e32 v6, 0, v4
	v_mul_f32_e32 v3, 0x4f7ffffe, v3
	v_cvt_u32_f32_e32 v3, v3
	v_mul_lo_u32 v6, v6, v3
	v_mul_hi_u32 v6, v3, v6
	v_add_u32_e32 v3, v3, v6
	s_waitcnt vmcnt(0) lgkmcnt(0)
	v_mul_hi_u32 v3, v5, v3
	v_mul_lo_u32 v6, v3, v4
	v_sub_u32_e32 v6, v5, v6
	v_cmp_ge_u32_e32 vcc, v6, v4
	v_add_u32_e32 v7, 1, v3
	s_nop 0
	v_cndmask_b32_e32 v3, v3, v7, vcc
	v_sub_u32_e32 v7, v6, v4
	v_cndmask_b32_e32 v6, v6, v7, vcc
	v_cmp_ge_u32_e32 vcc, v6, v4
	v_add_u32_e32 v6, 1, v3
	s_nop 0
	v_cndmask_b32_e32 v3, v3, v6, vcc
	v_add_u32_e32 v6, 1, v5
	v_mad_u64_u32 v[4:5], s[4:5], v4, v3, v[4:5]
	v_cmp_ne_u32_e32 vcc, v6, v4
	s_and_saveexec_b64 s[4:5], vcc
	s_xor_b64 s[4:5], exec, s[4:5]
	s_cbranch_execz .LBB0_457
	v_add_co_u32_e32 v4, vcc, 0x2000, v0
	s_nop 1
	v_addc_co_u32_e32 v5, vcc, 0, v1, vcc
	flat_load_dword v2, v[4:5] offset:1024 sc1
	s_waitcnt vmcnt(0) lgkmcnt(0)
	v_cmp_eq_u32_e32 vcc, v2, v3
	s_and_saveexec_b64 s[6:7], vcc
	s_cbranch_execz .LBB0_456
	s_mov_b64 s[10:11], 0x2400
	v_lshl_add_u64 v[0:1], v[0:1], 0, s[10:11]
	s_mov_b32 s9, 1
	s_mov_b64 s[10:11], 0
	s_branch .LBB0_447

.LBB0_482:
	s_lshr_b32 s7, s1, 7
	s_andn2_b64 vcc, exec, s[2:3]
	s_bfe_u32 s1, s1, 0x20005
	s_cbranch_vccnz .LBB0_484
	s_lshl_b32 s2, s7, 2
	s_add_i32 s2, s2, s66
	s_or_b32 s2, s2, s1
	s_mov_b32 s3, s8
	s_lshl_b64 s[2:3], s[2:3], 15
	s_add_u32 s5, s64, s2
	s_addc_u32 s9, s65, s3
	s_add_u32 s13, s67, s2
	s_addc_u32 s14, s68, s3
	s_lshl_b32 s2, s4, 10
	s_and_b32 s15, s2, 0xc00
	v_and_b32_e32 v1, 63, v1
	s_add_u32 s2, s5, s15
	v_lshlrev_b32_e32 v1, 4, v1
	s_addc_u32 s3, s9, 0
	s_add_i32 s26, s15, 0
	s_mov_b32 m0, s26
	s_nop 0
	global_load_lds_dwordx4 v1, s[2:3]
	s_or_b32 s27, s15, 0x1000
	s_add_u32 s10, s5, s27
	s_addc_u32 s11, s9, 0
	s_mov_b32 m0, s27
	s_nop 0
	global_load_lds_dwordx4 v1, s[10:11]
	s_or_b32 s5, s15, 0x2000
	s_add_u32 s9, s13, s5
	s_addc_u32 s11, s14, 0
	s_add_u32 s10, s9, 0xffffe000
	s_addc_u32 s11, s11, -1
	s_mov_b32 m0, s5
	s_nop 0
	global_load_lds_dwordx4 v1, s[10:11]
	s_or_b32 s5, s15, 0x3000
	s_add_u32 s9, s13, s5
	s_addc_u32 s11, s14, 0
	s_add_u32 s10, s9, 0xffffe000
	s_addc_u32 s11, s11, -1
	s_mov_b32 m0, s5
	s_nop 0
	global_load_lds_dwordx4 v1, s[10:11]
	s_add_u32 s10, s2, 0x2000
	s_addc_u32 s11, s3, 0
	s_add_i32 s5, s26, 0x5000
	s_mov_b32 m0, s5
	s_nop 0
	global_load_lds_dwordx4 v1, s[10:11]
	s_add_u32 s10, s2, 0x3000
	s_addc_u32 s11, s3, 0
	s_add_i32 s5, s26, 0x6000
	s_mov_b32 m0, s5
	s_nop 0
	global_load_lds_dwordx4 v1, s[10:11]
	s_add_u32 s5, s13, s15
	s_addc_u32 s9, s14, 0
	s_add_u32 s10, s5, 0x2000
	s_addc_u32 s11, s9, 0
	s_add_i32 s13, s26, 0x7000
	s_mov_b32 m0, s13
	s_nop 0
	global_load_lds_dwordx4 v1, s[10:11]
	s_add_u32 s10, s5, 0x3000
	s_addc_u32 s11, s9, 0
	s_add_i32 s13, s26, 0x8000
	s_mov_b32 m0, s13
	s_nop 0
	global_load_lds_dwordx4 v1, s[10:11]
	s_add_u32 s10, s2, 0x4000
	s_addc_u32 s11, s3, 0
	s_add_i32 s13, s26, 0xa000
	s_mov_b32 m0, s13
	s_nop 0
	global_load_lds_dwordx4 v1, s[10:11]
	s_add_u32 s10, s2, 0x5000
	s_addc_u32 s11, s3, 0
	s_add_i32 s13, s26, 0xb000
	s_mov_b32 m0, s13
	s_nop 0
	global_load_lds_dwordx4 v1, s[10:11]
	s_add_u32 s10, s5, 0x4000
	s_addc_u32 s11, s9, 0
	s_add_i32 s13, s26, 0xc000
	s_mov_b32 m0, s13
	s_nop 0
	global_load_lds_dwordx4 v1, s[10:11]
	s_add_u32 s10, s5, 0x5000
	s_addc_u32 s11, s9, 0
	s_add_i32 s13, s26, 0xd000
	s_mov_b32 m0, s13
	s_nop 0
	global_load_lds_dwordx4 v1, s[10:11]
	s_add_u32 s10, s2, 0x6000
	s_addc_u32 s11, s3, 0
	s_add_i32 s13, s26, 0xf000
	s_add_u32 s2, s2, 0x7000
	s_mov_b32 m0, s13
	s_nop 0
	global_load_lds_dwordx4 v1, s[10:11]
	s_addc_u32 s3, s3, 0
	s_add_i32 s10, s26, 0x10000
	s_mov_b32 m0, s10
	s_nop 0
	global_load_lds_dwordx4 v1, s[2:3]
	s_add_u32 s2, s5, 0x6000
	s_addc_u32 s3, s9, 0
	s_add_i32 s10, s26, 0x11000
	s_mov_b32 m0, s10
	s_nop 0
	global_load_lds_dwordx4 v1, s[2:3]
	s_add_u32 s2, s5, 0x7000
	s_addc_u32 s3, s9, 0
	s_add_i32 s26, s26, 0x12000
	s_mov_b32 m0, s26
	s_nop 0
	global_load_lds_dwordx4 v1, s[2:3]
	s_waitcnt vmcnt(8) lgkmcnt(0)
	s_barrier

.LBB0_489:
	s_add_i32 s10, s2, -8
	s_mul_i32 s44, s10, 0x180000
	s_mul_hi_u32 s43, s10, 0x180000
	s_add_u32 s28, s34, s44
	s_addc_u32 s29, s35, s43
	s_add_u32 s0, s38, s44
	s_addc_u32 s1, s39, s43
	s_mov_b32 s11, s8
	s_add_u32 s7, s0, 0x1800000
	s_addc_u32 s26, s1, 0
	s_lshl_b64 s[40:41], s[10:11], 20
	s_add_u32 s0, s69, s40
	s_addc_u32 s1, s70, s41
	s_lshl_b32 s6, s42, 3
	s_add_i32 s6, s3, s6
	v_bfe_u32 v0, v1, 5, 1
	s_mul_hi_i32 s9, s6, 12
	s_mul_i32 s6, s6, 12
	v_lshlrev_b32_e32 v4, 4, v1
	v_or_b32_e32 v2, s6, v0
	v_mov_b32_e32 v3, s9
	v_and_b32_e32 v172, 0x1f0, v4
	v_lshl_add_u64 v[4:5], s[28:29], 0, v[172:173]
	v_lshlrev_b64 v[2:3], 9, v[2:3]
	v_lshl_add_u64 v[2:3], v[4:5], 0, v[2:3]
	global_load_dwordx4 v[118:121], v[2:3], off nt
	global_load_dwordx4 v[114:117], v[2:3], off offset:1024 nt
	global_load_dwordx4 v[110:113], v[2:3], off offset:2048 nt
	global_load_dwordx4 v[106:109], v[2:3], off offset:3072 nt
	v_add_co_u32_e32 v2, vcc, 0x1000, v2
	v_and_b32_e32 v1, 63, v1
	s_nop 0
	v_addc_co_u32_e32 v3, vcc, 0, v3, vcc
	global_load_dwordx4 v[102:105], v[2:3], off nt
	global_load_dwordx4 v[98:101], v[2:3], off offset:1024 nt
	v_lshlrev_b32_e32 v170, 4, v1
	s_andn2_b64 vcc, exec, s[14:15]
	s_mov_b64 s[14:15], -1
	s_cbranch_vccnz .LBB0_491
	s_lshl_b32 s6, s3, 10
	s_and_b32 s6, s6, 0xc00
	s_add_u32 s14, s7, s6
	s_addc_u32 s15, s26, 0
	s_add_i32 s9, s6, 0
	s_mov_b32 m0, s9
	s_nop 0
	global_load_lds_dwordx4 v170, s[14:15]
	s_or_b32 s11, s6, 0x1000
	s_add_u32 s28, s7, s11
	s_addc_u32 s29, s26, 0
	s_mov_b32 m0, s11
	s_nop 0
	global_load_lds_dwordx4 v170, s[28:29]
	s_or_b32 s11, s6, 0x2000
	s_add_u32 s28, s7, s11
	s_addc_u32 s29, s26, 0
	s_mov_b32 m0, s11
	s_nop 0
	global_load_lds_dwordx4 v170, s[28:29]
	s_or_b32 s11, s6, 0x3000
	s_add_u32 s13, s0, s11
	s_addc_u32 s27, s1, 0
	s_add_u32 s28, s13, 0xffffd000
	s_addc_u32 s29, s27, -1
	s_mov_b32 m0, s11
	s_nop 0
	global_load_lds_dwordx4 v170, s[28:29]
	s_or_b32 s11, s6, 0x4000
	s_add_u32 s13, s0, s11
	s_addc_u32 s27, s1, 0
	s_add_u32 s28, s13, 0xffffd000
	s_addc_u32 s29, s27, -1
	s_mov_b32 m0, s11
	s_nop 0
	global_load_lds_dwordx4 v170, s[28:29]
	s_add_u32 s28, s14, 0x3000
	s_addc_u32 s29, s15, 0
	s_add_i32 s11, s9, 0x5000
	s_mov_b32 m0, s11
	s_nop 0
	global_load_lds_dwordx4 v170, s[28:29]
	s_add_u32 s28, s14, 0x4000
	s_addc_u32 s29, s15, 0
	s_add_i32 s11, s9, 0x6000
	s_mov_b32 m0, s11
	s_nop 0
	global_load_lds_dwordx4 v170, s[28:29]
	s_add_u32 s28, s14, 0x5000
	s_addc_u32 s29, s15, 0
	s_add_i32 s11, s9, 0x7000
	s_add_u32 s6, s0, s6
	s_mov_b32 m0, s11
	s_nop 0
	global_load_lds_dwordx4 v170, s[28:29]
	s_addc_u32 s11, s1, 0
	s_add_u32 s28, s6, 0x2000
	s_addc_u32 s29, s11, 0
	s_add_i32 s13, s9, 0x8000
	s_mov_b32 m0, s13
	s_nop 0
	global_load_lds_dwordx4 v170, s[28:29]
	s_add_u32 s28, s6, 0x3000
	s_addc_u32 s29, s11, 0
	s_add_i32 s13, s9, 0x9000
	s_mov_b32 m0, s13
	s_nop 0
	global_load_lds_dwordx4 v170, s[28:29]
	s_add_u32 s28, s14, 0x6000
	s_addc_u32 s29, s15, 0
	s_add_i32 s13, s9, 0xa000
	s_mov_b32 m0, s13
	s_nop 0
	global_load_lds_dwordx4 v170, s[28:29]
	s_add_u32 s28, s14, 0x7000
	s_addc_u32 s29, s15, 0
	s_add_i32 s13, s9, 0xb000
	s_mov_b32 m0, s13
	s_nop 0
	global_load_lds_dwordx4 v170, s[28:29]
	s_add_u32 s28, s14, 0x8000
	s_addc_u32 s29, s15, 0
	s_add_i32 s13, s9, 0xc000
	s_mov_b32 m0, s13
	s_nop 0
	global_load_lds_dwordx4 v170, s[28:29]
	s_add_u32 s28, s6, 0x4000
	s_addc_u32 s29, s11, 0
	s_add_i32 s13, s9, 0xd000
	s_mov_b32 m0, s13
	s_nop 0
	global_load_lds_dwordx4 v170, s[28:29]
	s_add_u32 s28, s6, 0x5000
	s_addc_u32 s29, s11, 0
	s_add_i32 s13, s9, 0xe000
	s_mov_b32 m0, s13
	s_nop 0
	global_load_lds_dwordx4 v170, s[28:29]
	s_add_u32 s28, s14, 0x9000
	s_addc_u32 s29, s15, 0
	s_add_i32 s13, s9, 0xf000
	s_mov_b32 m0, s13
	s_nop 0
	global_load_lds_dwordx4 v170, s[28:29]
	s_add_u32 s28, s14, 0xa000
	s_addc_u32 s29, s15, 0
	s_add_i32 s13, s9, 0x10000
	s_add_u32 s14, s14, 0xb000
	s_mov_b32 m0, s13
	s_nop 0
	global_load_lds_dwordx4 v170, s[28:29]
	s_addc_u32 s15, s15, 0
	s_add_i32 s13, s9, 0x11000
	s_mov_b32 m0, s13
	s_nop 0
	global_load_lds_dwordx4 v170, s[14:15]
	s_add_u32 s14, s6, 0x6000
	s_addc_u32 s15, s11, 0
	s_add_i32 s13, s9, 0x12000
	s_mov_b32 m0, s13
	s_nop 0
	global_load_lds_dwordx4 v170, s[14:15]
	s_add_u32 s14, s6, 0x7000
	s_addc_u32 s15, s11, 0
	s_add_i32 s9, s9, 0x13000
	s_mov_b32 m0, s9
	s_nop 0
	global_load_lds_dwordx4 v170, s[14:15]
	s_waitcnt vmcnt(10) lgkmcnt(0)
	s_barrier
	s_mov_b64 s[14:15], 0

.LBB0_496:
	s_mul_hi_u32 s9, s49, 0xaaaaaaab
	s_lshr_b32 s9, s9, 2
	s_mul_i32 s9, s9, 0x1e000
	s_sub_i32 s9, s28, s9
	s_cmp_ge_u32 s51, s46
	s_waitcnt vmcnt(0) lgkmcnt(0)
	s_barrier
	s_cselect_b64 s[10:11], -1, 0
	s_or_b64 s[10:11], s[4:5], s[10:11]
	s_and_b64 vcc, exec, s[10:11]
	s_cbranch_vccnz .LBB0_498
	s_add_u32 s13, s31, s28
	s_addc_u32 s14, s33, 0
	s_add_u32 s10, s13, 0x180c000
	s_addc_u32 s11, s14, 0
	s_add_i32 s15, s50, s9
	s_add_i32 s52, s15, 0x14000
	s_mov_b32 m0, s52
	s_nop 0
	global_load_lds_dwordx4 v170, s[10:11]
	s_add_u32 s10, s13, 0x180d000
	s_addc_u32 s11, s14, 0
	s_add_i32 s52, s15, 0x15000
	s_mov_b32 m0, s52
	s_nop 0
	global_load_lds_dwordx4 v170, s[10:11]
	s_add_u32 s10, s13, 0x180e000
	s_addc_u32 s11, s14, 0
	s_add_i32 s13, s15, 0x16000
	s_mov_b32 m0, s13
	s_nop 0
	global_load_lds_dwordx4 v170, s[10:11]
	s_add_u32 s13, s29, s28
	s_addc_u32 s14, s30, 0
	s_add_u32 s10, s13, 0xb708000
	s_addc_u32 s11, s14, 0
	s_add_i32 s52, s15, 0x17000
	s_mov_b32 m0, s52
	s_nop 0
	global_load_lds_dwordx4 v170, s[10:11]
	s_add_u32 s10, s13, 0xb709000
	s_addc_u32 s11, s14, 0
	s_add_i32 s13, s15, 0x18000
	s_add_i32 s13, s13, 0
	s_mov_b32 m0, s13
	s_nop 0
	global_load_lds_dwordx4 v170, s[10:11]
.LBB0_498:
	s_add_i32 s10, s51, 5
	s_cmp_ge_u32 s10, s47
	s_cselect_b64 s[10:11], -1, 0
	s_or_b64 s[10:11], s[4:5], s[10:11]
	s_and_b64 vcc, exec, s[10:11]
	s_cbranch_vccnz .LBB0_500
	s_add_u32 s13, s31, s28
	s_addc_u32 s14, s33, 0
	s_add_u32 s10, s13, 0x180f000
	s_addc_u32 s11, s14, 0
	s_add_i32 s9, s50, s9
	s_add_i32 s15, s9, 0x19000
	s_mov_b32 m0, s15
	s_nop 0
	global_load_lds_dwordx4 v170, s[10:11]
	s_add_u32 s10, s13, 0x1810000
	s_addc_u32 s11, s14, 0
	s_add_i32 s15, s9, 0x1a000
	s_mov_b32 m0, s15
	s_nop 0
	global_load_lds_dwordx4 v170, s[10:11]
	s_add_u32 s10, s13, 0x1811000
	s_addc_u32 s11, s14, 0
	s_add_i32 s13, s9, 0x1b000
	s_mov_b32 m0, s13
	s_nop 0
	global_load_lds_dwordx4 v170, s[10:11]
	s_add_u32 s13, s29, s28
	s_addc_u32 s14, s30, 0
	s_add_u32 s10, s13, 0xb70a000
	s_addc_u32 s11, s14, 0
	s_add_i32 s15, s9, 0x1c000
	s_mov_b32 m0, s15
	s_nop 0
	global_load_lds_dwordx4 v170, s[10:11]
	s_add_u32 s10, s13, 0xb70b000
	s_addc_u32 s11, s14, 0
	s_add_i32 s9, s9, 0x1d000
	s_add_i32 s9, s9, 0
	s_mov_b32 m0, s9
	s_nop 0
	global_load_lds_dwordx4 v170, s[10:11]

.LBB0_504:
	s_cmp_ge_u32 s9, s46
	s_waitcnt vmcnt(0) lgkmcnt(0)
	s_barrier
	s_cselect_b64 s[14:15], -1, 0
	s_or_b64 s[14:15], s[4:5], s[14:15]
	s_and_b64 vcc, exec, s[14:15]
	s_cbranch_vccnz .LBB0_506
	s_add_i32 s14, s9, 4
	s_mul_hi_u32 s11, s14, 0xaaaaaaab
	s_lshr_b32 s11, s11, 2
	s_mul_i32 s11, s11, 6
	s_mov_b32 s15, s8
	s_sub_i32 s11, s14, s11
	s_mul_hi_u32 s13, s14, 0x3000
	s_mul_i32 s28, s14, 0x3000
	s_lshl_b64 s[14:15], s[14:15], 13
	s_add_u32 s30, s7, s28
	s_addc_u32 s13, s26, s13
	s_lshl_b32 s28, s3, 10
	s_and_b32 s31, s28, 0xc00
	s_mulk_i32 s11, 0x5000
	s_add_u32 s28, s30, s31
	s_addc_u32 s29, s13, 0
	s_or_b32 s33, s11, s31
	s_mov_b32 m0, s33
	s_nop 0
	global_load_lds_dwordx4 v170, s[28:29]
	s_or_b32 s33, s31, 0x1000
	s_add_u32 s28, s30, s33
	s_addc_u32 s29, s13, 0
	s_or_b32 s33, s11, s33
	s_mov_b32 m0, s33
	s_nop 0
	global_load_lds_dwordx4 v170, s[28:29]
	s_or_b32 s33, s31, 0x2000
	s_add_u32 s28, s30, s33
	s_addc_u32 s29, s13, 0
	s_add_i32 s13, s11, s33
	s_mov_b32 m0, s13
	s_nop 0
	global_load_lds_dwordx4 v170, s[28:29]
	s_add_u32 s13, s0, s14
	s_addc_u32 s28, s1, s15
	s_or_b32 s29, s31, 0x3000
	s_add_u32 s14, s13, s29
	s_addc_u32 s15, s28, 0
	s_add_u32 s14, s14, 0xffffd000
	s_addc_u32 s15, s15, -1
	s_add_i32 s29, s11, s29
	s_add_i32 s29, s29, 0
	s_bitset1_b32 s31, 14
	s_add_u32 s13, s13, s31
	s_mov_b32 m0, s29
	s_nop 0
	global_load_lds_dwordx4 v170, s[14:15]
	s_addc_u32 s15, s28, 0
	s_add_u32 s14, s13, 0xffffd000
	s_addc_u32 s15, s15, -1
	s_add_i32 s11, s11, s31
	s_add_i32 s11, s11, 0
	s_mov_b32 m0, s11
	s_nop 0
	global_load_lds_dwordx4 v170, s[14:15]
.LBB0_506:
	s_add_i32 s14, s9, 5
	s_cmp_ge_u32 s14, s47
	s_cselect_b64 s[28:29], -1, 0
	s_or_b64 s[28:29], s[4:5], s[28:29]
	s_and_b64 vcc, exec, s[28:29]
	s_cbranch_vccnz .LBB0_508
	s_mul_hi_u32 s11, s14, 0xaaaaaaab
	s_lshr_b32 s11, s11, 2
	s_mul_i32 s11, s11, 6
	s_mov_b32 s15, s8
	s_sub_i32 s11, s14, s11
	s_mul_hi_u32 s13, s14, 0x3000
	s_mul_i32 s28, s14, 0x3000
	s_lshl_b64 s[14:15], s[14:15], 13
	s_add_u32 s7, s7, s28
	s_addc_u32 s13, s26, s13
	s_lshl_b32 s26, s3, 10
	s_and_b32 s26, s26, 0xc00
	s_mulk_i32 s11, 0x5000
	s_add_u32 s28, s7, s26
	s_addc_u32 s29, s13, 0
	s_or_b32 s30, s11, s26
	s_mov_b32 m0, s30
	s_nop 0
	global_load_lds_dwordx4 v170, s[28:29]
	s_or_b32 s30, s26, 0x1000
	s_add_u32 s28, s7, s30
	s_addc_u32 s29, s13, 0
	s_add_i32 s30, s11, s30
	s_mov_b32 m0, s30
	s_nop 0
	global_load_lds_dwordx4 v170, s[28:29]
	s_or_b32 s30, s26, 0x2000
	s_add_u32 s28, s7, s30
	s_addc_u32 s29, s13, 0
	s_add_i32 s7, s11, s30
	s_mov_b32 m0, s7
	s_nop 0
	global_load_lds_dwordx4 v170, s[28:29]
	s_add_u32 s7, s0, s14
	s_addc_u32 s13, s1, s15
	s_or_b32 s14, s26, 0x3000
	s_add_u32 s0, s7, s14
	s_addc_u32 s1, s13, 0
	s_add_u32 s0, s0, 0xffffd000
	s_addc_u32 s1, s1, -1
	s_add_i32 s14, s11, s14
	s_add_i32 s14, s14, 0
	s_bitset1_b32 s26, 14
	s_mov_b32 m0, s14
	s_nop 0
	global_load_lds_dwordx4 v170, s[0:1]
	s_add_u32 s0, s7, s26
	s_addc_u32 s1, s13, 0
	s_add_u32 s0, s0, 0xffffd000
	s_addc_u32 s1, s1, -1
	s_add_i32 s7, s11, s26
	s_add_i32 s7, s7, 0
	s_mov_b32 m0, s7
	s_nop 0
	global_load_lds_dwordx4 v170, s[0:1]

.LBB0_515:
	s_cmp_ge_u32 s10, s46
	s_waitcnt vmcnt(0) lgkmcnt(0)
	s_barrier
	s_cselect_b64 s[28:29], -1, 0
	s_or_b64 s[28:29], s[4:5], s[28:29]
	s_and_b64 vcc, exec, s[28:29]
	s_cbranch_vccnz .LBB0_517
	s_mul_hi_u32 s27, s11, 0xaaaaaaab
	s_lshr_b32 s27, s27, 2
	s_add_u32 s30, s7, s0
	s_addc_u32 s31, s9, 0
	s_add_u32 s28, s30, 0x180c000
	s_mul_i32 s27, s27, 0x1e000
	s_addc_u32 s29, s31, 0
	s_add_i32 s33, s13, s14
	s_sub_i32 s27, s33, s27
	s_add_i32 s33, s27, 0x14000
	s_mov_b32 m0, s33
	s_nop 0
	global_load_lds_dwordx4 v170, s[28:29]
	s_add_u32 s28, s30, 0x180d000
	s_addc_u32 s29, s31, 0
	s_add_i32 s33, s27, 0x15000
	s_mov_b32 m0, s33
	s_nop 0
	global_load_lds_dwordx4 v170, s[28:29]
	s_add_u32 s28, s30, 0x180e000
	s_addc_u32 s29, s31, 0
	s_add_i32 s30, s27, 0x16000
	s_mov_b32 m0, s30
	s_nop 0
	global_load_lds_dwordx4 v170, s[28:29]
	s_add_u32 s30, s1, s0
	s_addc_u32 s31, s6, 0
	s_add_u32 s28, s30, 0xb708000
	s_addc_u32 s29, s31, 0
	s_add_i32 s33, s27, 0x17000
	s_mov_b32 m0, s33
	s_nop 0
	global_load_lds_dwordx4 v170, s[28:29]
	s_add_u32 s28, s30, 0xb709000
	s_addc_u32 s29, s31, 0
	s_add_i32 s27, s27, 0x18000
	s_add_i32 s27, s27, 0
	s_mov_b32 m0, s27
	s_nop 0
	global_load_lds_dwordx4 v170, s[28:29]
.LBB0_517:
	s_add_i32 s10, s10, 5
	s_cmp_ge_u32 s10, s47
	s_cselect_b64 s[28:29], -1, 0
	s_or_b64 s[28:29], s[4:5], s[28:29]
	s_and_b64 vcc, exec, s[28:29]
	s_cbranch_vccnz .LBB0_514
	s_mul_hi_u32 s27, s26, 0xaaaaaaab
	s_lshr_b32 s27, s27, 2
	s_add_u32 s30, s7, s0
	s_addc_u32 s31, s9, 0
	s_add_u32 s28, s30, 0x180f000
	s_mul_i32 s27, s27, 0x1e000
	s_addc_u32 s29, s31, 0
	s_add_i32 s33, s13, s14
	s_sub_i32 s27, s33, s27
	s_add_i32 s33, s27, 0x19000
	s_mov_b32 m0, s33
	s_nop 0
	global_load_lds_dwordx4 v170, s[28:29]
	s_add_u32 s28, s30, 0x1810000
	s_addc_u32 s29, s31, 0
	s_add_i32 s33, s27, 0x1a000
	s_mov_b32 m0, s33
	s_nop 0
	global_load_lds_dwordx4 v170, s[28:29]
	s_add_u32 s28, s30, 0x1811000
	s_addc_u32 s29, s31, 0
	s_add_i32 s30, s27, 0x1b000
	s_mov_b32 m0, s30
	s_nop 0
	global_load_lds_dwordx4 v170, s[28:29]
	s_add_u32 s30, s1, s0
	s_addc_u32 s31, s6, 0
	s_add_u32 s28, s30, 0xb70a000
	s_addc_u32 s29, s31, 0
	s_add_i32 s33, s27, 0x1c000
	s_mov_b32 m0, s33
	s_nop 0
	global_load_lds_dwordx4 v170, s[28:29]
	s_add_u32 s28, s30, 0xb70b000
	s_addc_u32 s29, s31, 0
	s_add_i32 s27, s27, 0x1d000
	s_add_i32 s27, s27, 0
	s_mov_b32 m0, s27
	s_nop 0
	global_load_lds_dwordx4 v170, s[28:29]
	s_branch .LBB0_514

.LBB0_523:
	s_mul_hi_u32 s13, s9, 0xaaaaaaab
	s_lshr_b32 s13, s13, 2
	s_mul_i32 s13, s13, 0x1e000
	s_sub_i32 s15, 0x18000, s13
	s_cmp_ge_u32 s14, s46
	s_waitcnt vmcnt(0) lgkmcnt(0)
	s_barrier
	s_cselect_b64 s[26:27], -1, 0
	s_or_b64 s[26:27], s[4:5], s[26:27]
	s_and_b64 vcc, exec, s[26:27]
	s_cbranch_vccnz .LBB0_525
	s_add_u32 s28, s6, s0
	s_addc_u32 s29, s7, 0
	s_add_u32 s26, s28, 0x180c000
	s_addc_u32 s27, s29, 0
	s_add_i32 s30, s0, s10
	s_sub_i32 s31, s30, s13
	s_add_i32 s33, s31, 0x14000
	s_mov_b32 m0, s33
	s_nop 0
	global_load_lds_dwordx4 v170, s[26:27]
	s_add_u32 s26, s28, 0x180d000
	s_addc_u32 s27, s29, 0
	s_add_i32 s33, s31, 0x15000
	s_mov_b32 m0, s33
	s_nop 0
	global_load_lds_dwordx4 v170, s[26:27]
	s_add_u32 s26, s28, 0x180e000
	s_addc_u32 s27, s29, 0
	s_add_i32 s28, s31, 0x16000
	s_mov_b32 m0, s28
	s_nop 0
	global_load_lds_dwordx4 v170, s[26:27]
	s_add_u32 s28, s1, s0
	s_addc_u32 s29, s3, 0
	s_add_u32 s26, s28, 0xb708000
	s_addc_u32 s27, s29, 0
	s_add_i32 s31, s31, 0x17000
	s_mov_b32 m0, s31
	s_nop 0
	global_load_lds_dwordx4 v170, s[26:27]
	s_add_u32 s26, s28, 0xb709000
	s_addc_u32 s27, s29, 0
	s_add_i32 s28, s30, s15
	s_add_i32 s28, s28, 0
	s_mov_b32 m0, s28
	s_nop 0
	global_load_lds_dwordx4 v170, s[26:27]
.LBB0_525:
	s_add_i32 s14, s14, 5
	s_cmp_ge_u32 s14, s47
	s_cselect_b64 s[26:27], -1, 0
	s_or_b64 s[26:27], s[4:5], s[26:27]
	s_and_b64 vcc, exec, s[26:27]
	s_cbranch_vccnz .LBB0_522
	s_add_i32 s28, s0, s10
	s_add_i32 s15, s15, s28
	s_add_u32 s29, s6, s0
	s_addc_u32 s30, s7, 0
	s_add_u32 s26, s29, 0x180f000
	s_addc_u32 s27, s30, 0
	s_addk_i32 s15, 0x1000
	s_mov_b32 m0, s15
	s_nop 0
	global_load_lds_dwordx4 v170, s[26:27]
	s_add_u32 s26, s29, 0x1810000
	s_addc_u32 s27, s30, 0
	s_sub_i32 s13, s28, s13
	s_add_i32 s15, s13, 0x1a000
	s_mov_b32 m0, s15
	s_nop 0
	global_load_lds_dwordx4 v170, s[26:27]
	s_add_u32 s26, s29, 0x1811000
	s_addc_u32 s27, s30, 0
	s_add_i32 s15, s13, 0x1b000
	s_mov_b32 m0, s15
	s_nop 0
	global_load_lds_dwordx4 v170, s[26:27]
	s_add_u32 s15, s1, s0
	s_addc_u32 s28, s3, 0
	s_add_u32 s26, s15, 0xb70a000
	s_addc_u32 s27, s28, 0
	s_add_i32 s29, s13, 0x1c000
	s_mov_b32 m0, s29
	s_nop 0
	global_load_lds_dwordx4 v170, s[26:27]
	s_add_u32 s26, s15, 0xb70b000
	s_addc_u32 s27, s28, 0
	s_add_i32 s13, s13, 0x1d000
	s_add_i32 s13, s13, 0
	s_mov_b32 m0, s13
	s_nop 0
	global_load_lds_dwordx4 v170, s[26:27]
	s_branch .LBB0_522

.LBB0_535:
	s_lshl_b32 s2, s6, 10
	s_and_b32 s4, s2, 0xc00
	s_add_u32 s2, s0, s4
	s_addc_u32 s3, s1, 0
	s_add_u32 s2, s2, 0x2000
	s_addc_u32 s3, s3, 0
	s_add_i32 s5, s4, 0
	s_add_i32 s9, s5, 0xa000
	s_mov_b32 m0, s9
	s_nop 0
	global_load_lds_dwordx4 v1, s[2:3]
	s_add_u32 s2, s13, s4
	s_addc_u32 s3, s30, 0
	s_add_u32 s2, s2, 0x2000
	s_addc_u32 s3, s3, 0
	s_add_i32 s9, s5, 0xb000
	s_add_u32 s4, s29, s4
	s_mov_b32 m0, s9
	s_nop 0
	global_load_lds_dwordx4 v1, s[2:3]
	s_addc_u32 s9, s33, 0
	s_add_u32 s2, s4, 0x4000
	s_addc_u32 s3, s9, 0
	s_add_i32 s11, s5, 0xc000
	s_mov_b32 m0, s11
	s_nop 0
	global_load_lds_dwordx4 v1, s[2:3]
	s_add_u32 s2, s4, 0x5000
	s_addc_u32 s3, s9, 0
	s_add_i32 s5, s5, 0xd000
	s_mov_b32 m0, s5
	s_nop 0
	global_load_lds_dwordx4 v1, s[2:3]

.LBB0_545:
	s_add_i32 s2, s9, 3
	s_cmp_ge_u32 s2, s27
	s_cselect_b64 s[2:3], -1, 0
	s_or_b64 s[2:3], s[14:15], s[2:3]
	s_and_b64 vcc, exec, s[2:3]
	s_cbranch_vccnz .LBB0_547
	s_add_i32 s2, s43, 2
	s_and_b32 s2, s2, 3
	s_add_u32 s11, s44, s5
	s_addc_u32 s48, s45, 0
	s_mul_i32 s10, s2, 0x5000
	s_add_u32 s2, s11, 0xcf03000
	s_addc_u32 s3, s48, 0
	s_or_b32 s49, s10, s5
	s_mov_b32 m0, s49
	s_nop 0
	global_load_lds_dwordx4 v1, s[2:3]
	s_add_u32 s2, s11, 0xcf83000
	s_addc_u32 s3, s48, 0
	s_add_i32 s11, s10, s40
	s_mov_b32 m0, s11
	s_nop 0
	global_load_lds_dwordx4 v1, s[2:3]
	s_add_u32 s11, s46, s5
	s_addc_u32 s48, s47, 0
	s_add_u32 s2, s11, 0xd706000
	s_addc_u32 s3, s48, 0
	s_add_i32 s49, s10, s41
	s_mov_b32 m0, s49
	s_nop 0
	global_load_lds_dwordx4 v1, s[2:3]
	s_add_u32 s2, s11, 0xd707000
	s_addc_u32 s3, s48, 0
	s_add_i32 s10, s10, s42
	s_add_i32 s10, s10, 0
	s_mov_b32 m0, s10
	s_nop 0
	global_load_lds_dwordx4 v1, s[2:3]

.LBB0_549:
	s_lshl_b32 s2, s6, 10
	s_and_b32 s9, s2, 0xc00
	s_add_u32 s2, s0, s9
	s_addc_u32 s3, s1, 0
	s_add_i32 s11, s9, 0
	s_mov_b32 m0, s11
	s_nop 0
	global_load_lds_dwordx4 v1, s[2:3]
	s_or_b32 s26, s9, 0x1000
	s_add_u32 s4, s13, s26
	s_addc_u32 s5, s30, 0
	s_add_u32 s4, s4, 0xfffff000
	s_addc_u32 s5, s5, -1
	s_mov_b32 m0, s26
	s_nop 0
	global_load_lds_dwordx4 v1, s[4:5]
	s_or_b32 s26, s9, 0x2000
	s_add_u32 s4, s29, s26
	s_addc_u32 s5, s33, 0
	s_add_u32 s4, s4, 0xffffe000
	s_addc_u32 s5, s5, -1
	s_mov_b32 m0, s26
	s_nop 0
	global_load_lds_dwordx4 v1, s[4:5]
	s_or_b32 s26, s9, 0x3000
	s_add_u32 s4, s29, s26
	s_addc_u32 s5, s33, 0
	s_add_u32 s4, s4, 0xffffe000
	s_addc_u32 s5, s5, -1
	s_add_i32 s26, s26, 0
	s_add_u32 s2, s2, 0x1000
	s_mov_b32 m0, s26
	s_nop 0
	global_load_lds_dwordx4 v1, s[4:5]
	s_addc_u32 s3, s3, 0
	s_add_i32 s4, s11, 0x5000
	s_mov_b32 m0, s4
	s_nop 0
	global_load_lds_dwordx4 v1, s[2:3]
	s_add_u32 s2, s13, s9
	s_addc_u32 s3, s30, 0
	s_add_u32 s2, s2, 0x1000
	s_addc_u32 s3, s3, 0
	s_add_i32 s4, s11, 0x6000
	s_mov_b32 m0, s4
	s_nop 0
	global_load_lds_dwordx4 v1, s[2:3]
	s_add_u32 s4, s29, s9
	s_addc_u32 s5, s33, 0
	s_add_u32 s2, s4, 0x2000
	s_addc_u32 s3, s5, 0
	s_add_i32 s9, s11, 0x7000
	s_mov_b32 m0, s9
	s_nop 0
	global_load_lds_dwordx4 v1, s[2:3]
	s_add_u32 s2, s4, 0x3000
	s_addc_u32 s3, s5, 0
	s_add_i32 s11, s11, 0x8000
	s_mov_b32 m0, s11
	s_nop 0
	global_load_lds_dwordx4 v1, s[2:3]
	s_waitcnt vmcnt(4) lgkmcnt(0)
	s_barrier
	s_cbranch_execnz .LBB0_534

.LBB0_559:
	s_add_i32 s2, s26, 3
	s_cmp_ge_u32 s2, s27
	s_cselect_b64 s[10:11], -1, 0
	s_or_b64 s[10:11], s[14:15], s[10:11]
	v_writelane_b32 v242, s79, 9
	s_and_b64 vcc, exec, s[10:11]
	v_writelane_b32 v242, s53, 10
	s_cbranch_vccnz .LBB0_561
	s_and_b32 s3, s2, 3
	s_mul_i32 s5, s3, 0x5000
	s_mov_b32 s3, s8
	s_lshl_b64 s[10:11], s[2:3], 13
	s_lshl_b64 s[2:3], s[2:3], 12
	s_add_u32 s9, s0, s2
	s_addc_u32 s41, s1, s3
	s_lshl_b32 s40, s6, 10
	s_and_b32 s42, s40, 0xc00
	s_add_u32 s40, s9, s42
	s_addc_u32 s41, s41, 0
	s_or_b32 s9, s5, s42
	s_add_i32 s9, s9, 0
	s_add_u32 s2, s13, s2
	s_mov_b32 m0, s9
	s_nop 0
	global_load_lds_dwordx4 v1, s[40:41]
	s_addc_u32 s3, s30, s3
	s_or_b32 s9, s42, 0x1000
	s_add_u32 s2, s2, s9
	s_addc_u32 s3, s3, 0
	s_add_u32 s2, s2, 0xfffff000
	s_addc_u32 s3, s3, -1
	s_add_i32 s9, s5, s9
	s_mov_b32 m0, s9
	s_nop 0
	global_load_lds_dwordx4 v1, s[2:3]
	s_add_u32 s9, s29, s10
	s_addc_u32 s10, s33, s11
	s_or_b32 s11, s42, 0x2000
	s_add_u32 s2, s9, s11
	s_addc_u32 s3, s10, 0
	s_add_u32 s2, s2, 0xffffe000
	s_addc_u32 s3, s3, -1
	s_add_i32 s11, s5, s11
	s_mov_b32 m0, s11
	s_nop 0
	global_load_lds_dwordx4 v1, s[2:3]
	s_or_b32 s11, s42, 0x3000
	s_add_u32 s2, s9, s11
	s_addc_u32 s3, s10, 0
	s_add_u32 s2, s2, 0xffffe000
	s_addc_u32 s3, s3, -1
	s_add_i32 s5, s5, s11
	s_add_i32 s5, s5, 0
	s_mov_b32 m0, s5
	s_nop 0
	global_load_lds_dwordx4 v1, s[2:3]

.LBB0_572:
	s_cmp_ge_u32 s26, s7
	s_cselect_b64 s[2:3], -1, 0
	s_or_b64 s[2:3], s[14:15], s[2:3]
	s_and_b64 vcc, exec, s[2:3]
	s_cbranch_vccnz .LBB0_563
	s_and_b32 s3, s26, 3
	s_add_i32 s2, s26, 4
	s_mul_i32 s30, s3, 0x5000
	s_mov_b32 s3, s8
	s_lshl_b64 s[40:41], s[2:3], 13
	s_lshl_b64 s[2:3], s[2:3], 12
	s_add_u32 s42, s0, s2
	s_addc_u32 s43, s1, s3
	s_or_b32 s44, s30, s4
	s_add_i32 s44, s44, 0
	s_add_u32 s2, s9, s2
	s_addc_u32 s3, s10, s3
	s_add_u32 s2, s2, 0xfffff000
	s_mov_b32 m0, s44
	s_nop 0
	global_load_lds_dwordx4 v1, s[42:43]
	s_addc_u32 s3, s3, -1
	s_add_i32 s42, s30, s5
	s_add_i32 s42, s42, 0
	s_add_u32 s40, s29, s40
	s_addc_u32 s41, s33, s41
	s_mov_b32 m0, s42
	s_nop 0
	global_load_lds_dwordx4 v1, s[2:3]
	s_add_u32 s2, s40, s11
	s_addc_u32 s3, s41, 0
	s_add_u32 s2, s2, 0xffffe000
	s_addc_u32 s3, s3, -1
	s_add_i32 s42, s30, s11
	s_mov_b32 m0, s42
	s_nop 0
	global_load_lds_dwordx4 v1, s[2:3]
	s_add_u32 s2, s40, s13
	s_addc_u32 s3, s41, 0
	s_add_u32 s2, s2, 0xffffe000
	s_addc_u32 s3, s3, -1
	s_add_i32 s30, s30, s13
	s_add_i32 s30, s30, 0
	s_mov_b32 m0, s30
	s_nop 0
	global_load_lds_dwordx4 v1, s[2:3]
	s_branch .LBB0_563

.LBB0_585:
	s_cmp_ge_u32 s11, s27
	s_cselect_b64 s[2:3], -1, 0
	s_or_b64 s[2:3], s[14:15], s[2:3]
	s_and_b64 vcc, exec, s[2:3]
	s_cbranch_vccnz .LBB0_577
	s_and_b32 s2, s11, 3
	s_add_u32 s26, s6, s0
	s_addc_u32 s29, s7, 0
	s_mul_i32 s13, s2, 0x5000
	s_add_u32 s2, s26, 0xcf03000
	s_addc_u32 s3, s29, 0
	s_or_b32 s30, s13, s0
	s_mov_b32 m0, s30
	s_nop 0
	global_load_lds_dwordx4 v1, s[2:3]
	s_add_u32 s2, s26, 0xcf83000
	s_addc_u32 s3, s29, 0
	s_add_i32 s26, s13, s1
	s_mov_b32 m0, s26
	s_nop 0
	global_load_lds_dwordx4 v1, s[2:3]
	s_add_u32 s26, s9, s0
	s_addc_u32 s29, s10, 0
	s_add_u32 s2, s26, 0xd706000
	s_addc_u32 s3, s29, 0
	s_add_i32 s30, s13, s4
	s_mov_b32 m0, s30
	s_nop 0
	global_load_lds_dwordx4 v1, s[2:3]
	s_add_u32 s2, s26, 0xd707000
	s_addc_u32 s3, s29, 0
	s_add_i32 s13, s13, s5
	s_add_i32 s13, s13, 0
	s_mov_b32 m0, s13
	s_nop 0
	global_load_lds_dwordx4 v1, s[2:3]
	s_branch .LBB0_577
